# FFN hidden (HID) epilogue stores write-through sc1, plus phase-B rewrites
# speedup vs baseline: 1.0053x; 1.0023x over previous
.LBB0_495:
	s_waitcnt lgkmcnt(0)
	v_mul_f32_e32 v146, 0xbfb8aa3b, v144
	v_pk_mul_f32 v[148:149], v[126:127], v[146:147] op_sel_hi:[1,0]
	v_mul_f32_e32 v144, v144, v144
	v_exp_f32_e32 v148, v148
	v_exp_f32_e32 v149, v149
	v_pk_mul_f32 v[122:123], v[126:127], v[122:123]
	v_pk_mul_f32 v[124:125], v[128:129], v[124:125]
	v_pk_mul_f32 v[120:121], v[116:117], v[120:121]
	v_pk_add_f32 v[148:149], v[148:149], 1.0 op_sel_hi:[1,0]
	v_lshl_or_b32 v134, s90, 7, v141
	v_rcp_f32_e32 v148, v148
	v_rcp_f32_e32 v149, v149
	v_ashrrev_i32_e32 v135, 31, v134
	s_mov_b64 s[68:69], -1
	s_and_b64 vcc, exec, s[52:53]
	v_pk_mul_f32 v[126:127], v[144:145], v[148:149] op_sel_hi:[0,1]
	v_pk_mul_f32 v[122:123], v[122:123], v[126:127]
	v_pk_mul_f32 v[126:127], v[128:129], v[146:147] op_sel_hi:[1,0]
	s_nop 0
	v_exp_f32_e32 v126, v126
	v_exp_f32_e32 v127, v127
	s_nop 0
	v_pk_add_f32 v[126:127], v[126:127], 1.0 op_sel_hi:[1,0]
	s_nop 0
	v_rcp_f32_e32 v126, v126
	v_rcp_f32_e32 v127, v127
	s_nop 0
	v_pk_mul_f32 v[126:127], v[144:145], v[126:127] op_sel_hi:[0,1]
	v_pk_mul_f32 v[124:125], v[124:125], v[126:127]
	v_pk_mul_f32 v[126:127], v[114:115], v[146:147] op_sel_hi:[1,0]
	v_pk_mul_f32 v[114:115], v[114:115], v[118:119]
	v_exp_f32_e32 v126, v126
	v_exp_f32_e32 v127, v127
	s_nop 0
	v_pk_add_f32 v[126:127], v[126:127], 1.0 op_sel_hi:[1,0]
	s_nop 0
	v_rcp_f32_e32 v126, v126
	v_rcp_f32_e32 v127, v127
	s_nop 0
	v_pk_mul_f32 v[118:119], v[144:145], v[126:127] op_sel_hi:[0,1]
	v_pk_mul_f32 v[118:119], v[114:115], v[118:119]
	v_pk_mul_f32 v[114:115], v[116:117], v[146:147] op_sel_hi:[1,0]
	s_nop 0
	v_exp_f32_e32 v114, v114
	v_exp_f32_e32 v115, v115
	s_nop 0
	v_pk_add_f32 v[114:115], v[114:115], 1.0 op_sel_hi:[1,0]
	s_nop 0
	v_rcp_f32_e32 v114, v114
	v_rcp_f32_e32 v115, v115
	s_nop 0
	v_pk_mul_f32 v[114:115], v[144:145], v[114:115] op_sel_hi:[0,1]
	v_pk_mul_f32 v[120:121], v[120:121], v[114:115]
	v_cvt_pk_bf16_f32 v114, v122, v123
	v_cvt_pk_bf16_f32 v115, v124, v125
	v_cvt_pk_bf16_f32 v116, v118, v119
	v_mov_b64_e32 v[118:119], s[40:41]
	v_mad_u64_u32 v[118:119], s[20:21], v136, s17, v[118:119]
	v_cvt_pk_bf16_f32 v117, v120, v121
	v_mov_b32_e32 v120, v119
	v_mad_u64_u32 v[120:121], s[20:21], v137, s17, v[120:121]
	v_mov_b32_e32 v119, v120
	v_lshl_add_u64 v[118:119], v[134:135], 1, v[118:119]
	global_store_dwordx4 v[118:119], v[114:117], off sc1
	s_nop 1
	v_or_b32_e32 v114, 16, v136
	v_ashrrev_i32_e32 v115, 31, v114
	s_cbranch_vccnz .LBB0_497
	ds_read_b32 v116, v143 offset:64
	s_mov_b64 s[68:69], 0

.LBB0_499:
	s_waitcnt lgkmcnt(0)
	v_mul_f32_e32 v118, 0xbfb8aa3b, v116
	v_pk_mul_f32 v[120:121], v[110:111], v[118:119] op_sel_hi:[1,0]
	v_mul_f32_e32 v116, v116, v116
	v_exp_f32_e32 v120, v120
	v_exp_f32_e32 v121, v121
	v_pk_mul_f32 v[106:107], v[110:111], v[106:107]
	v_pk_mul_f32 v[108:109], v[112:113], v[108:109]
	v_pk_mul_f32 v[104:105], v[100:101], v[104:105]
	v_pk_add_f32 v[120:121], v[120:121], 1.0 op_sel_hi:[1,0]
	s_mov_b64 s[68:69], -1
	v_rcp_f32_e32 v120, v120
	v_rcp_f32_e32 v121, v121
	s_and_b64 vcc, exec, s[52:53]
	v_pk_mul_f32 v[110:111], v[116:117], v[120:121] op_sel_hi:[0,1]
	v_pk_mul_f32 v[106:107], v[106:107], v[110:111]
	v_pk_mul_f32 v[110:111], v[112:113], v[118:119] op_sel_hi:[1,0]
	s_nop 0
	v_exp_f32_e32 v110, v110
	v_exp_f32_e32 v111, v111
	s_nop 0
	v_pk_add_f32 v[110:111], v[110:111], 1.0 op_sel_hi:[1,0]
	s_nop 0
	v_rcp_f32_e32 v110, v110
	v_rcp_f32_e32 v111, v111
	s_nop 0
	v_pk_mul_f32 v[110:111], v[116:117], v[110:111] op_sel_hi:[0,1]
	v_pk_mul_f32 v[108:109], v[108:109], v[110:111]
	v_pk_mul_f32 v[110:111], v[98:99], v[118:119] op_sel_hi:[1,0]
	v_pk_mul_f32 v[98:99], v[98:99], v[102:103]
	v_exp_f32_e32 v110, v110
	v_exp_f32_e32 v111, v111
	s_nop 0
	v_pk_add_f32 v[110:111], v[110:111], 1.0 op_sel_hi:[1,0]
	s_nop 0
	v_rcp_f32_e32 v110, v110
	v_rcp_f32_e32 v111, v111
	s_nop 0
	v_pk_mul_f32 v[102:103], v[116:117], v[110:111] op_sel_hi:[0,1]
	v_pk_mul_f32 v[102:103], v[98:99], v[102:103]
	v_pk_mul_f32 v[98:99], v[100:101], v[118:119] op_sel_hi:[1,0]
	s_nop 0
	v_exp_f32_e32 v98, v98
	v_exp_f32_e32 v99, v99
	s_nop 0
	v_pk_add_f32 v[98:99], v[98:99], 1.0 op_sel_hi:[1,0]
	s_nop 0
	v_rcp_f32_e32 v98, v98
	v_rcp_f32_e32 v99, v99
	s_nop 0
	v_pk_mul_f32 v[98:99], v[116:117], v[98:99] op_sel_hi:[0,1]
	v_pk_mul_f32 v[104:105], v[104:105], v[98:99]
	v_cvt_pk_bf16_f32 v98, v106, v107
	v_cvt_pk_bf16_f32 v99, v108, v109
	v_cvt_pk_bf16_f32 v100, v102, v103
	v_mov_b64_e32 v[102:103], s[40:41]
	v_mad_u64_u32 v[102:103], s[20:21], v114, s17, v[102:103]
	v_cvt_pk_bf16_f32 v101, v104, v105
	v_mov_b32_e32 v104, v103
	v_mad_u64_u32 v[104:105], s[20:21], v115, s17, v[104:105]
	v_mov_b32_e32 v103, v104
	v_lshl_add_u64 v[102:103], v[134:135], 1, v[102:103]
	global_store_dwordx4 v[102:103], v[98:101], off sc1
	s_nop 1
	v_or_b32_e32 v98, 32, v136
	v_ashrrev_i32_e32 v99, 31, v98
	s_cbranch_vccnz .LBB0_501
	ds_read_b32 v100, v143 offset:128
	s_mov_b64 s[68:69], 0

.LBB0_503:
	s_waitcnt lgkmcnt(0)
	v_mul_f32_e32 v102, 0xbfb8aa3b, v100
	v_pk_mul_f32 v[104:105], v[94:95], v[102:103] op_sel_hi:[1,0]
	v_mul_f32_e32 v100, v100, v100
	v_exp_f32_e32 v104, v104
	v_exp_f32_e32 v105, v105
	v_pk_mul_f32 v[90:91], v[94:95], v[90:91]
	v_pk_mul_f32 v[92:93], v[96:97], v[92:93]
	v_pk_mul_f32 v[88:89], v[84:85], v[88:89]
	v_pk_add_f32 v[104:105], v[104:105], 1.0 op_sel_hi:[1,0]
	s_mov_b64 s[68:69], -1
	v_rcp_f32_e32 v104, v104
	v_rcp_f32_e32 v105, v105
	s_and_b64 vcc, exec, s[52:53]
	v_pk_mul_f32 v[94:95], v[100:101], v[104:105] op_sel_hi:[0,1]
	v_pk_mul_f32 v[90:91], v[90:91], v[94:95]
	v_pk_mul_f32 v[94:95], v[96:97], v[102:103] op_sel_hi:[1,0]
	s_nop 0
	v_exp_f32_e32 v94, v94
	v_exp_f32_e32 v95, v95
	s_nop 0
	v_pk_add_f32 v[94:95], v[94:95], 1.0 op_sel_hi:[1,0]
	s_nop 0
	v_rcp_f32_e32 v94, v94
	v_rcp_f32_e32 v95, v95
	s_nop 0
	v_pk_mul_f32 v[94:95], v[100:101], v[94:95] op_sel_hi:[0,1]
	v_pk_mul_f32 v[92:93], v[92:93], v[94:95]
	v_pk_mul_f32 v[94:95], v[82:83], v[102:103] op_sel_hi:[1,0]
	v_pk_mul_f32 v[82:83], v[82:83], v[86:87]
	v_exp_f32_e32 v94, v94
	v_exp_f32_e32 v95, v95
	s_nop 0
	v_pk_add_f32 v[94:95], v[94:95], 1.0 op_sel_hi:[1,0]
	s_nop 0
	v_rcp_f32_e32 v94, v94
	v_rcp_f32_e32 v95, v95
	s_nop 0
	v_pk_mul_f32 v[86:87], v[100:101], v[94:95] op_sel_hi:[0,1]
	v_pk_mul_f32 v[86:87], v[82:83], v[86:87]
	v_pk_mul_f32 v[82:83], v[84:85], v[102:103] op_sel_hi:[1,0]
	s_nop 0
	v_exp_f32_e32 v82, v82
	v_exp_f32_e32 v83, v83
	s_nop 0
	v_pk_add_f32 v[82:83], v[82:83], 1.0 op_sel_hi:[1,0]
	s_nop 0
	v_rcp_f32_e32 v82, v82
	v_rcp_f32_e32 v83, v83
	s_nop 0
	v_pk_mul_f32 v[82:83], v[100:101], v[82:83] op_sel_hi:[0,1]
	v_pk_mul_f32 v[88:89], v[88:89], v[82:83]
	v_cvt_pk_bf16_f32 v82, v90, v91
	v_cvt_pk_bf16_f32 v83, v92, v93
	v_cvt_pk_bf16_f32 v84, v86, v87
	v_mov_b64_e32 v[86:87], s[40:41]
	v_mad_u64_u32 v[86:87], s[20:21], v98, s17, v[86:87]
	v_cvt_pk_bf16_f32 v85, v88, v89
	v_mov_b32_e32 v88, v87
	v_mad_u64_u32 v[88:89], s[20:21], v99, s17, v[88:89]
	v_mov_b32_e32 v87, v88
	v_lshl_add_u64 v[86:87], v[134:135], 1, v[86:87]
	global_store_dwordx4 v[86:87], v[82:85], off sc1
	s_nop 1
	v_or_b32_e32 v82, 48, v136
	v_ashrrev_i32_e32 v83, 31, v82
	s_cbranch_vccnz .LBB0_505
	ds_read_b32 v84, v143 offset:192
	s_mov_b64 s[68:69], 0

.LBB0_507:
	s_waitcnt lgkmcnt(0)
	v_mul_f32_e32 v86, 0xbfb8aa3b, v84
	v_pk_mul_f32 v[88:89], v[78:79], v[86:87] op_sel_hi:[1,0]
	v_mul_f32_e32 v84, v84, v84
	v_exp_f32_e32 v88, v88
	v_exp_f32_e32 v89, v89
	v_pk_mul_f32 v[74:75], v[78:79], v[74:75]
	v_pk_mul_f32 v[76:77], v[80:81], v[76:77]
	v_pk_mul_f32 v[72:73], v[68:69], v[72:73]
	v_pk_add_f32 v[88:89], v[88:89], 1.0 op_sel_hi:[1,0]
	s_mov_b64 s[68:69], -1
	v_rcp_f32_e32 v88, v88
	v_rcp_f32_e32 v89, v89
	s_and_b64 vcc, exec, s[52:53]
	v_pk_mul_f32 v[78:79], v[84:85], v[88:89] op_sel_hi:[0,1]
	v_pk_mul_f32 v[74:75], v[74:75], v[78:79]
	v_pk_mul_f32 v[78:79], v[80:81], v[86:87] op_sel_hi:[1,0]
	s_nop 0
	v_exp_f32_e32 v78, v78
	v_exp_f32_e32 v79, v79
	s_nop 0
	v_pk_add_f32 v[78:79], v[78:79], 1.0 op_sel_hi:[1,0]
	s_nop 0
	v_rcp_f32_e32 v78, v78
	v_rcp_f32_e32 v79, v79
	s_nop 0
	v_pk_mul_f32 v[78:79], v[84:85], v[78:79] op_sel_hi:[0,1]
	v_pk_mul_f32 v[76:77], v[76:77], v[78:79]
	v_pk_mul_f32 v[78:79], v[66:67], v[86:87] op_sel_hi:[1,0]
	v_pk_mul_f32 v[66:67], v[66:67], v[70:71]
	v_exp_f32_e32 v78, v78
	v_exp_f32_e32 v79, v79
	s_nop 0
	v_pk_add_f32 v[78:79], v[78:79], 1.0 op_sel_hi:[1,0]
	s_nop 0
	v_rcp_f32_e32 v78, v78
	v_rcp_f32_e32 v79, v79
	s_nop 0
	v_pk_mul_f32 v[70:71], v[84:85], v[78:79] op_sel_hi:[0,1]
	v_pk_mul_f32 v[70:71], v[66:67], v[70:71]
	v_pk_mul_f32 v[66:67], v[68:69], v[86:87] op_sel_hi:[1,0]
	s_nop 0
	v_exp_f32_e32 v66, v66
	v_exp_f32_e32 v67, v67
	s_nop 0
	v_pk_add_f32 v[66:67], v[66:67], 1.0 op_sel_hi:[1,0]
	s_nop 0
	v_rcp_f32_e32 v66, v66
	v_rcp_f32_e32 v67, v67
	s_nop 0
	v_pk_mul_f32 v[66:67], v[84:85], v[66:67] op_sel_hi:[0,1]
	v_pk_mul_f32 v[72:73], v[72:73], v[66:67]
	v_cvt_pk_bf16_f32 v66, v74, v75
	v_cvt_pk_bf16_f32 v67, v76, v77
	v_cvt_pk_bf16_f32 v68, v70, v71
	v_mov_b64_e32 v[70:71], s[40:41]
	v_mad_u64_u32 v[70:71], s[20:21], v82, s17, v[70:71]
	v_cvt_pk_bf16_f32 v69, v72, v73
	v_mov_b32_e32 v72, v71
	v_mad_u64_u32 v[72:73], s[20:21], v83, s17, v[72:73]
	v_mov_b32_e32 v71, v72
	v_lshl_add_u64 v[70:71], v[134:135], 1, v[70:71]
	global_store_dwordx4 v[70:71], v[66:69], off sc1
	s_nop 1
	v_add_u32_e32 v66, 0x80, v136
	v_ashrrev_i32_e32 v67, 31, v66
	s_cbranch_vccnz .LBB0_509
	ds_read_b32 v68, v143 offset:512
	s_mov_b64 s[68:69], 0

.LBB0_511:
	s_waitcnt lgkmcnt(0)
	v_mul_f32_e32 v70, 0xbfb8aa3b, v68
	v_pk_mul_f32 v[72:73], v[62:63], v[70:71] op_sel_hi:[1,0]
	v_mul_f32_e32 v68, v68, v68
	v_exp_f32_e32 v72, v72
	v_exp_f32_e32 v73, v73
	v_pk_mul_f32 v[58:59], v[62:63], v[58:59]
	v_pk_mul_f32 v[60:61], v[64:65], v[60:61]
	v_pk_mul_f32 v[56:57], v[52:53], v[56:57]
	v_pk_add_f32 v[72:73], v[72:73], 1.0 op_sel_hi:[1,0]
	s_mov_b64 s[68:69], -1
	v_rcp_f32_e32 v72, v72
	v_rcp_f32_e32 v73, v73
	s_and_b64 vcc, exec, s[52:53]
	v_pk_mul_f32 v[62:63], v[68:69], v[72:73] op_sel_hi:[0,1]
	v_pk_mul_f32 v[58:59], v[58:59], v[62:63]
	v_pk_mul_f32 v[62:63], v[64:65], v[70:71] op_sel_hi:[1,0]
	s_nop 0
	v_exp_f32_e32 v62, v62
	v_exp_f32_e32 v63, v63
	s_nop 0
	v_pk_add_f32 v[62:63], v[62:63], 1.0 op_sel_hi:[1,0]
	s_nop 0
	v_rcp_f32_e32 v62, v62
	v_rcp_f32_e32 v63, v63
	s_nop 0
	v_pk_mul_f32 v[62:63], v[68:69], v[62:63] op_sel_hi:[0,1]
	v_pk_mul_f32 v[60:61], v[60:61], v[62:63]
	v_pk_mul_f32 v[62:63], v[50:51], v[70:71] op_sel_hi:[1,0]
	v_pk_mul_f32 v[50:51], v[50:51], v[54:55]
	v_exp_f32_e32 v62, v62
	v_exp_f32_e32 v63, v63
	s_nop 0
	v_pk_add_f32 v[62:63], v[62:63], 1.0 op_sel_hi:[1,0]
	s_nop 0
	v_rcp_f32_e32 v62, v62
	v_rcp_f32_e32 v63, v63
	s_nop 0
	v_pk_mul_f32 v[54:55], v[68:69], v[62:63] op_sel_hi:[0,1]
	v_pk_mul_f32 v[54:55], v[50:51], v[54:55]
	v_pk_mul_f32 v[50:51], v[52:53], v[70:71] op_sel_hi:[1,0]
	s_nop 0
	v_exp_f32_e32 v50, v50
	v_exp_f32_e32 v51, v51
	s_nop 0
	v_pk_add_f32 v[50:51], v[50:51], 1.0 op_sel_hi:[1,0]
	s_nop 0
	v_rcp_f32_e32 v50, v50
	v_rcp_f32_e32 v51, v51
	s_nop 0
	v_pk_mul_f32 v[50:51], v[68:69], v[50:51] op_sel_hi:[0,1]
	v_pk_mul_f32 v[56:57], v[56:57], v[50:51]
	v_cvt_pk_bf16_f32 v50, v58, v59
	v_cvt_pk_bf16_f32 v51, v60, v61
	v_cvt_pk_bf16_f32 v52, v54, v55
	v_mov_b64_e32 v[54:55], s[40:41]
	v_mad_u64_u32 v[54:55], s[20:21], v66, s17, v[54:55]
	v_cvt_pk_bf16_f32 v53, v56, v57
	v_mov_b32_e32 v56, v55
	v_mad_u64_u32 v[56:57], s[20:21], v67, s17, v[56:57]
	v_mov_b32_e32 v55, v56
	v_lshl_add_u64 v[54:55], v[134:135], 1, v[54:55]
	global_store_dwordx4 v[54:55], v[50:53], off sc1
	s_nop 1
	v_add_u32_e32 v50, 0x90, v136
	v_ashrrev_i32_e32 v51, 31, v50
	s_cbranch_vccnz .LBB0_513
	ds_read_b32 v52, v143 offset:576
	s_mov_b64 s[68:69], 0

.LBB0_515:
	s_waitcnt lgkmcnt(0)
	v_mul_f32_e32 v54, 0xbfb8aa3b, v52
	v_pk_mul_f32 v[56:57], v[46:47], v[54:55] op_sel_hi:[1,0]
	v_mul_f32_e32 v52, v52, v52
	v_exp_f32_e32 v56, v56
	v_exp_f32_e32 v57, v57
	v_pk_mul_f32 v[42:43], v[46:47], v[42:43]
	v_pk_mul_f32 v[44:45], v[48:49], v[44:45]
	v_pk_mul_f32 v[40:41], v[36:37], v[40:41]
	v_pk_add_f32 v[56:57], v[56:57], 1.0 op_sel_hi:[1,0]
	s_mov_b64 s[68:69], -1
	v_rcp_f32_e32 v56, v56
	v_rcp_f32_e32 v57, v57
	s_and_b64 vcc, exec, s[52:53]
	v_pk_mul_f32 v[46:47], v[52:53], v[56:57] op_sel_hi:[0,1]
	v_pk_mul_f32 v[42:43], v[42:43], v[46:47]
	v_pk_mul_f32 v[46:47], v[48:49], v[54:55] op_sel_hi:[1,0]
	s_nop 0
	v_exp_f32_e32 v46, v46
	v_exp_f32_e32 v47, v47
	s_nop 0
	v_pk_add_f32 v[46:47], v[46:47], 1.0 op_sel_hi:[1,0]
	s_nop 0
	v_rcp_f32_e32 v46, v46
	v_rcp_f32_e32 v47, v47
	s_nop 0
	v_pk_mul_f32 v[46:47], v[52:53], v[46:47] op_sel_hi:[0,1]
	v_pk_mul_f32 v[44:45], v[44:45], v[46:47]
	v_pk_mul_f32 v[46:47], v[34:35], v[54:55] op_sel_hi:[1,0]
	v_pk_mul_f32 v[34:35], v[34:35], v[38:39]
	v_exp_f32_e32 v46, v46
	v_exp_f32_e32 v47, v47
	s_nop 0
	v_pk_add_f32 v[46:47], v[46:47], 1.0 op_sel_hi:[1,0]
	s_nop 0
	v_rcp_f32_e32 v46, v46
	v_rcp_f32_e32 v47, v47
	s_nop 0
	v_pk_mul_f32 v[38:39], v[52:53], v[46:47] op_sel_hi:[0,1]
	v_pk_mul_f32 v[38:39], v[34:35], v[38:39]
	v_pk_mul_f32 v[34:35], v[36:37], v[54:55] op_sel_hi:[1,0]
	s_nop 0
	v_exp_f32_e32 v34, v34
	v_exp_f32_e32 v35, v35
	s_nop 0
	v_pk_add_f32 v[34:35], v[34:35], 1.0 op_sel_hi:[1,0]
	s_nop 0
	v_rcp_f32_e32 v34, v34
	v_rcp_f32_e32 v35, v35
	s_nop 0
	v_pk_mul_f32 v[34:35], v[52:53], v[34:35] op_sel_hi:[0,1]
	v_pk_mul_f32 v[40:41], v[40:41], v[34:35]
	v_cvt_pk_bf16_f32 v34, v42, v43
	v_cvt_pk_bf16_f32 v35, v44, v45
	v_cvt_pk_bf16_f32 v36, v38, v39
	v_mov_b64_e32 v[38:39], s[40:41]
	v_mad_u64_u32 v[38:39], s[20:21], v50, s17, v[38:39]
	v_cvt_pk_bf16_f32 v37, v40, v41
	v_mov_b32_e32 v40, v39
	v_mad_u64_u32 v[40:41], s[20:21], v51, s17, v[40:41]
	v_mov_b32_e32 v39, v40
	v_lshl_add_u64 v[38:39], v[134:135], 1, v[38:39]
	global_store_dwordx4 v[38:39], v[34:37], off sc1
	s_nop 1
	v_add_u32_e32 v34, 0xa0, v136
	v_ashrrev_i32_e32 v35, 31, v34
	s_cbranch_vccnz .LBB0_517
	ds_read_b32 v36, v143 offset:640
	s_mov_b64 s[68:69], 0

.LBB0_519:
	s_waitcnt lgkmcnt(0)
	v_mul_f32_e32 v38, 0xbfb8aa3b, v36
	v_pk_mul_f32 v[40:41], v[30:31], v[38:39] op_sel_hi:[1,0]
	v_mul_f32_e32 v36, v36, v36
	v_exp_f32_e32 v40, v40
	v_exp_f32_e32 v41, v41
	v_pk_mul_f32 v[26:27], v[30:31], v[26:27]
	v_pk_mul_f32 v[28:29], v[32:33], v[28:29]
	v_pk_mul_f32 v[24:25], v[20:21], v[24:25]
	v_pk_add_f32 v[40:41], v[40:41], 1.0 op_sel_hi:[1,0]
	s_mov_b64 s[68:69], -1
	v_rcp_f32_e32 v40, v40
	v_rcp_f32_e32 v41, v41
	s_and_b64 vcc, exec, s[52:53]
	v_pk_mul_f32 v[30:31], v[36:37], v[40:41] op_sel_hi:[0,1]
	v_pk_mul_f32 v[26:27], v[26:27], v[30:31]
	v_pk_mul_f32 v[30:31], v[32:33], v[38:39] op_sel_hi:[1,0]
	s_nop 0
	v_exp_f32_e32 v30, v30
	v_exp_f32_e32 v31, v31
	s_nop 0
	v_pk_add_f32 v[30:31], v[30:31], 1.0 op_sel_hi:[1,0]
	s_nop 0
	v_rcp_f32_e32 v30, v30
	v_rcp_f32_e32 v31, v31
	s_nop 0
	v_pk_mul_f32 v[30:31], v[36:37], v[30:31] op_sel_hi:[0,1]
	v_pk_mul_f32 v[28:29], v[28:29], v[30:31]
	v_pk_mul_f32 v[30:31], v[18:19], v[38:39] op_sel_hi:[1,0]
	v_pk_mul_f32 v[18:19], v[18:19], v[22:23]
	v_exp_f32_e32 v30, v30
	v_exp_f32_e32 v31, v31
	s_nop 0
	v_pk_add_f32 v[30:31], v[30:31], 1.0 op_sel_hi:[1,0]
	s_nop 0
	v_rcp_f32_e32 v30, v30
	v_rcp_f32_e32 v31, v31
	s_nop 0
	v_pk_mul_f32 v[22:23], v[36:37], v[30:31] op_sel_hi:[0,1]
	v_pk_mul_f32 v[22:23], v[18:19], v[22:23]
	v_pk_mul_f32 v[18:19], v[20:21], v[38:39] op_sel_hi:[1,0]
	s_nop 0
	v_exp_f32_e32 v18, v18
	v_exp_f32_e32 v19, v19
	s_nop 0
	v_pk_add_f32 v[18:19], v[18:19], 1.0 op_sel_hi:[1,0]
	s_nop 0
	v_rcp_f32_e32 v18, v18
	v_rcp_f32_e32 v19, v19
	s_nop 0
	v_pk_mul_f32 v[18:19], v[36:37], v[18:19] op_sel_hi:[0,1]
	v_pk_mul_f32 v[24:25], v[24:25], v[18:19]
	v_cvt_pk_bf16_f32 v18, v26, v27
	v_cvt_pk_bf16_f32 v19, v28, v29
	v_cvt_pk_bf16_f32 v20, v22, v23
	v_mov_b64_e32 v[22:23], s[40:41]
	v_mad_u64_u32 v[22:23], s[20:21], v34, s17, v[22:23]
	v_cvt_pk_bf16_f32 v21, v24, v25
	v_mov_b32_e32 v24, v23
	v_mad_u64_u32 v[24:25], s[20:21], v35, s17, v[24:25]
	v_mov_b32_e32 v23, v24
	v_lshl_add_u64 v[22:23], v[134:135], 1, v[22:23]
	global_store_dwordx4 v[22:23], v[18:21], off sc1
	s_nop 1
	v_add_u32_e32 v18, 0xb0, v136
	v_ashrrev_i32_e32 v19, 31, v18
	s_cbranch_vccnz .LBB0_521
	ds_read_b32 v20, v143 offset:704
	s_mov_b64 s[68:69], 0

.LBB0_523:
	s_waitcnt lgkmcnt(0)
	v_mul_f32_e32 v22, 0xbfb8aa3b, v20
	v_pk_mul_f32 v[24:25], v[14:15], v[22:23] op_sel_hi:[1,0]
	v_mul_f32_e32 v20, v20, v20
	v_exp_f32_e32 v24, v24
	v_exp_f32_e32 v25, v25
	v_pk_mul_f32 v[10:11], v[14:15], v[10:11]
	v_pk_mul_f32 v[12:13], v[16:17], v[12:13]
	v_pk_mul_f32 v[2:3], v[6:7], v[2:3]
	v_pk_add_f32 v[24:25], v[24:25], 1.0 op_sel_hi:[1,0]
	v_pk_mul_f32 v[4:5], v[8:9], v[4:5]
	v_rcp_f32_e32 v24, v24
	v_rcp_f32_e32 v25, v25
	s_mov_b64 s[68:69], -1
	s_andn2_b64 vcc, exec, s[54:55]
	v_pk_mul_f32 v[14:15], v[20:21], v[24:25] op_sel_hi:[0,1]
	v_pk_mul_f32 v[10:11], v[10:11], v[14:15]
	v_pk_mul_f32 v[14:15], v[16:17], v[22:23] op_sel_hi:[1,0]
	s_nop 0
	v_exp_f32_e32 v14, v14
	v_exp_f32_e32 v15, v15
	s_nop 0
	v_pk_add_f32 v[14:15], v[14:15], 1.0 op_sel_hi:[1,0]
	s_nop 0
	v_rcp_f32_e32 v14, v14
	v_rcp_f32_e32 v15, v15
	s_nop 0
	v_pk_mul_f32 v[14:15], v[20:21], v[14:15] op_sel_hi:[0,1]
	v_pk_mul_f32 v[12:13], v[12:13], v[14:15]
	v_pk_mul_f32 v[14:15], v[6:7], v[22:23] op_sel_hi:[1,0]
	s_nop 0
	v_exp_f32_e32 v14, v14
	v_exp_f32_e32 v15, v15
	s_nop 0
	v_pk_add_f32 v[14:15], v[14:15], 1.0 op_sel_hi:[1,0]
	s_nop 0
	v_rcp_f32_e32 v14, v14
	v_rcp_f32_e32 v15, v15
	s_nop 0
	v_pk_mul_f32 v[6:7], v[20:21], v[14:15] op_sel_hi:[0,1]
	v_pk_mul_f32 v[6:7], v[2:3], v[6:7]
	v_pk_mul_f32 v[2:3], v[8:9], v[22:23] op_sel_hi:[1,0]
	s_nop 0
	v_exp_f32_e32 v2, v2
	v_exp_f32_e32 v3, v3
	s_nop 0
	v_pk_add_f32 v[2:3], v[2:3], 1.0 op_sel_hi:[1,0]
	s_nop 0
	v_rcp_f32_e32 v2, v2
	v_rcp_f32_e32 v3, v3
	s_nop 0
	v_pk_mul_f32 v[2:3], v[20:21], v[2:3] op_sel_hi:[0,1]
	v_pk_mul_f32 v[8:9], v[4:5], v[2:3]
	v_cvt_pk_bf16_f32 v2, v10, v11
	v_cvt_pk_bf16_f32 v3, v12, v13
	v_cvt_pk_bf16_f32 v4, v6, v7
	v_mov_b64_e32 v[6:7], s[40:41]
	v_mad_u64_u32 v[6:7], s[20:21], v18, s17, v[6:7]
	v_cvt_pk_bf16_f32 v5, v8, v9
	v_mov_b32_e32 v8, v7
	v_mad_u64_u32 v[8:9], s[20:21], v19, s17, v[8:9]
	v_mov_b32_e32 v7, v8
	v_lshl_add_u64 v[6:7], v[134:135], 1, v[6:7]
	global_store_dwordx4 v[6:7], v[2:5], off sc1
	s_cbranch_vccnz .LBB0_484
	s_andn2_b64 vcc, exec, s[6:7]
	s_cbranch_vccnz .LBB0_483
	s_barrier
	s_branch .LBB0_483
